# P0: waves 0-3 run all weight-transpose items, waves 4-7 go straight to the row copy (overlap latency-bound transposes with bandwidth-bound copy)
# speedup vs baseline: 1.0102x; 1.0102x over previous
; #define LAS __attribute__((address_space(3)))
; __device__ __forceinline__ Frame fresh(const Frame& F0) { Frame F = F0; int t = threadIdx.x; asm volatile("" : "+v"(t)); F.tid = t; F.lane = t & 63; F.wave = __builtin_amdgcn_readfirstlane(t >> 6); return F; }
; __device__ __forceinline__ void p0_prologue(const Params& p, const Frame& F0) {
;     const Frame F = fresh(F0);
;     LAS float* scr = (LAS float*)(F.lds + F.wave * 16384);
;     const int gw = F.vcu * 8 + F.wave, NGW = F.G * 8;
;     bf16_t* Win_t = (bf16_t*)(p.ws + WS_WIN); bf16_t* Glu_t = (bf16_t*)(p.ws + WS_GLU); bf16_t* Wout_t = (bf16_t*)(p.ws + WS_WOUT); bf16_t* Wq_t = (bf16_t*)(p.ws + WS_WQ);
;     bf16_t* Wkv_t = (bf16_t*)(p.ws + WS_WKV); bf16_t* Wo_t = (bf16_t*)(p.ws + WS_WO); bf16_t* W1_t = (bf16_t*)(p.ws + WS_W1); bf16_t* W2_t = (bf16_t*)(p.ws + WS_W2);
;     bf16_t* Vt = (bf16_t*)(p.ws + WS_VT);
;     constexpr int I_IN = 16 * 48, I_GLU = 8 * 16, I_SQ = 16 * 32, I_1 = 16 * 128, I_2 = 64 * 32, I_VT = 16 * 4 * 32;
;     constexpr int NITEMS = I_IN + I_GLU + 5 * I_SQ + I_1 + I_2 + I_VT;
;     for (int it = gw; it < NITEMS; it += NGW) {
;         int r = it;
;         if (r < I_IN) { const int kb = r / 48, nb = r % 48; transpose_item(p.in[8], DM, DIN, Win_t, DM, 64 * kb, 32 * nb, win_dest_row(32 * nb), scr, F.lane); continue; } r -= I_IN;
.LBB0_7:
	s_or_b64 exec, exec, s[4:5]
	s_load_dwordx16 s[4:19], s[0:1], 0x0
	s_add_u32 s3, s58, 0x2d00000
	v_mov_b32_e32 v34, v202
	s_mov_b32 s62, s20
	s_waitcnt lgkmcnt(0)
	v_writelane_b32 v254, s4, 22
	v_and_b32_e32 v1, 7, v34
	s_nop 0
	v_writelane_b32 v254, s5, 23
	v_writelane_b32 v254, s6, 24
	v_writelane_b32 v254, s7, 25
	v_writelane_b32 v254, s8, 26
	v_writelane_b32 v254, s9, 27
	v_writelane_b32 v254, s10, 28
	v_writelane_b32 v254, s11, 29
	v_writelane_b32 v254, s12, 30
	v_writelane_b32 v254, s13, 31
	v_writelane_b32 v254, s14, 32
	v_writelane_b32 v254, s15, 33
	v_writelane_b32 v254, s16, 34
	v_writelane_b32 v254, s17, 35
	v_writelane_b32 v254, s18, 36
	v_writelane_b32 v254, s19, 37
	s_load_dwordx16 s[4:19], s[0:1], 0x40
	s_waitcnt lgkmcnt(0)
	v_writelane_b32 v254, s4, 38
	s_nop 1
	v_writelane_b32 v254, s5, 39
	v_writelane_b32 v254, s6, 40
	v_writelane_b32 v254, s7, 41
	v_writelane_b32 v254, s8, 42
	v_writelane_b32 v254, s9, 43
	v_writelane_b32 v254, s10, 44
	v_writelane_b32 v254, s11, 45
	v_writelane_b32 v254, s12, 46
	v_writelane_b32 v254, s13, 47
	v_writelane_b32 v254, s14, 48
	v_writelane_b32 v254, s15, 49
	v_writelane_b32 v254, s16, 50
	v_writelane_b32 v254, s17, 51
	v_writelane_b32 v254, s18, 52
	v_writelane_b32 v254, s19, 53
	v_writelane_b32 v254, s3, 54
	s_addc_u32 s3, s59, 0
	v_writelane_b32 v254, s3, 55
	v_readfirstlane_b32 s3, v34
	s_ashr_i32 s3, s3, 6
	s_lshl_b32 s4, s20, 3
	s_add_i32 s26, s3, s4
	s_cmp_gt_u32 s3, 3
	s_cselect_b32 s26, 0x7fff, s26
	s_lshl_b32 s33, s92, 3
	v_writelane_b32 v254, s4, 56
	s_add_u32 s4, s58, 0x500000
	s_addc_u32 s5, s59, 0
	v_writelane_b32 v254, s4, 57
	s_nop 1
	v_writelane_b32 v254, s5, 58
	s_add_u32 s4, s58, 0x700000
	s_addc_u32 s5, s59, 0
	v_writelane_b32 v254, s4, 59
	s_add_u32 s20, s58, 0x900000
	s_addc_u32 s21, s59, 0
	v_writelane_b32 v254, s5, 60
	s_load_dwordx16 s[4:19], s[0:1], 0x80
	s_cmpk_gt_i32 s26, 0x257f
	s_waitcnt lgkmcnt(0)
	v_writelane_b32 v254, s4, 61
	s_nop 1
	v_writelane_b32 v255, s7, 0
	v_writelane_b32 v255, s8, 1
	v_writelane_b32 v255, s9, 2
	v_writelane_b32 v255, s10, 3
	v_writelane_b32 v255, s11, 4
	v_writelane_b32 v255, s12, 5
	v_writelane_b32 v255, s13, 6
	v_writelane_b32 v255, s14, 7
	v_writelane_b32 v255, s15, 8
	v_writelane_b32 v255, s16, 9
	v_writelane_b32 v255, s17, 10
	v_writelane_b32 v255, s18, 11
	v_writelane_b32 v255, s19, 12
	v_writelane_b32 v254, s5, 62
	v_writelane_b32 v255, s20, 13
	v_writelane_b32 v254, s6, 63
	s_nop 0
	v_writelane_b32 v255, s21, 14
	s_cbranch_scc1 .LBB0_156
	s_lshl_b32 s0, s3, 14
	v_bfe_u32 v9, v34, 5, 1
	v_and_b32_e32 v2, 31, v34
	s_add_i32 s0, s0, 0
	v_lshlrev_b32_e32 v4, 2, v2
	v_mul_u32_u24_e32 v3, 0x84, v9
	v_bfe_u32 v10, v34, 3, 3
	v_mov_b32_e32 v7, 0
	v_add3_u32 v11, s0, v4, v3
	v_mul_u32_u24_e32 v3, 0x420, v1
	v_lshlrev_b32_e32 v5, 2, v10
	v_readlane_b32 s4, v254, 61
	v_add3_u32 v13, s0, v3, v5
	v_mov_b32_e32 v5, v7
	v_readlane_b32 s5, v254, 62
	v_readlane_b32 s6, v254, 63
	v_readlane_b32 s7, v255, 0
	v_readlane_b32 s8, v255, 1
	v_readlane_b32 s9, v255, 2
	v_readlane_b32 s10, v255, 3
	v_readlane_b32 s11, v255, 4
	v_readlane_b32 s12, v255, 5
	v_readlane_b32 s13, v255, 6
	v_readlane_b32 s14, v255, 7
	v_readlane_b32 s15, v255, 8
	v_readlane_b32 s16, v255, 9
	v_readlane_b32 s17, v255, 10
	v_readlane_b32 s18, v255, 11
	v_readlane_b32 s19, v255, 12
	v_lshl_add_u64 v[30:31], s[6:7], 0, v[4:5]
	v_readlane_b32 s4, v254, 38
	s_add_u32 s96, s58, 0x3620000
	v_readlane_b32 s5, v254, 39
	v_readlane_b32 s6, v254, 40
	v_readlane_b32 s7, v254, 41
	v_readlane_b32 s8, v254, 42
	v_readlane_b32 s9, v254, 43
	v_readlane_b32 s10, v254, 44
	v_readlane_b32 s11, v254, 45
	v_readlane_b32 s12, v254, 46
	v_readlane_b32 s13, v254, 47
	v_readlane_b32 s14, v254, 48
	v_readlane_b32 s15, v254, 49
	v_readlane_b32 s16, v254, 50
	v_readlane_b32 s17, v254, 51
	v_readlane_b32 s18, v254, 52
	v_readlane_b32 s19, v254, 53
	s_addc_u32 s97, s59, 0
	v_lshl_add_u64 v[32:33], s[4:5], 0, v[4:5]
	s_add_u32 s40, s58, 0x3660000
	v_readlane_b32 s4, v254, 3
	s_addc_u32 s41, s59, 0
	v_readlane_b32 s16, v254, 15
	v_readlane_b32 s17, v254, 16
	v_readlane_b32 s6, v254, 5
	v_readlane_b32 s7, v254, 6
	v_readlane_b32 s8, v254, 7
	s_cmp_lg_u64 s[16:17], 0
	v_lshlrev_b32_e32 v6, 4, v1
	v_readlane_b32 s9, v254, 8
	s_cselect_b64 s[6:7], -1, 0
	s_add_u32 s8, s58, 0x3600000
	v_lshl_add_u64 v[24:25], s[58:59], 0, v[6:7]
	s_mov_b64 s[0:1], 0x1700000
	v_readlane_b32 s10, v254, 9
	s_addc_u32 s9, s59, 0
	v_lshl_add_u64 v[18:19], v[24:25], 0, s[0:1]
	s_mov_b64 s[0:1], 0xf00000
	v_readlane_b32 s11, v254, 10
	s_add_u32 s10, s58, 0x3610000
	v_lshl_add_u64 v[20:21], v[24:25], 0, s[0:1]
	s_mov_b64 s[0:1], 0x400000
	v_readlane_b32 s5, v254, 4
	s_addc_u32 s11, s59, 0
	v_lshl_add_u64 v[22:23], v[24:25], 0, s[0:1]
	s_mov_b64 s[0:1], 0x100000
	s_cmp_lg_u64 s[4:5], 0
	v_lshlrev_b32_e32 v8, 3, v1
	v_lshl_add_u64 v[24:25], v[24:25], 0, s[0:1]
	v_readlane_b32 s12, v254, 11
	v_readlane_b32 s13, v254, 12
	v_readlane_b32 s14, v254, 13
	v_readlane_b32 s15, v254, 14
	v_readlane_b32 s19, v254, 18
	s_cselect_b64 s[16:17], -1, 0
	s_lshl_b32 s0, s26, 6
	v_lshlrev_b32_e32 v36, 2, v2
	v_mbcnt_lo_u32_b32 v2, -1, 0
	v_or_b32_e32 v12, 8, v10
	v_or_b32_e32 v14, 16, v10
	v_or_b32_e32 v16, 24, v10
	v_lshl_add_u64 v[26:27], s[48:49], 0, v[4:5]
	v_lshl_add_u64 v[28:29], s[44:45], 0, v[4:5]
	s_lshl_b32 s27, s26, 5
	s_lshl_b32 s28, s33, 5
	s_add_i32 s29, s0, 0x7ffffc00
	s_lshl_b32 s30, s33, 6
	s_lshl_b32 s31, s26, 1
	s_lshl_b32 s34, s33, 1
	s_lshl_b32 s35, s26, 2
	s_lshl_b32 s36, s33, 2
	s_movk_i32 s14, 0x2000
	s_movk_i32 s15, 0x4000
	v_add_u32_e32 v15, 0x400, v11
	v_add_u32_e32 v17, 0x800, v11
	v_add_u32_e32 v35, 0xc00, v11
	v_add_u32_e32 v48, 0x1000, v11
	v_add_u32_e32 v49, 0x1400, v11
	v_add_u32_e32 v50, 0x1800, v11
	v_add_u32_e32 v51, 0x1c00, v11
	v_lshlrev_b32_e32 v6, 1, v8
	v_mbcnt_hi_u32_b32 v52, -1, v2
	s_movk_i32 s63, 0x6000
	s_mov_b32 s64, 0x8000
	s_mov_b32 s65, 0xa000
	s_mov_b32 s66, 0xc000
	s_mov_b32 s67, 0xe000
	s_mov_b32 s68, 0x10000
	s_mov_b32 s69, 0x12000
	s_mov_b32 s70, 0x14000
	s_mov_b32 s71, 0x16000
	s_mov_b32 s72, 0x18000
	s_mov_b32 s73, 0x1a000
	s_mov_b32 s74, 0x1c000
	s_mov_b32 s75, 0x1e000
	s_mov_b32 s94, 0x20000
	s_mov_b32 s12, 0x26000
	s_mov_b32 s13, 0x28000
	s_mov_b32 s42, 0x2a000
	s_mov_b32 s43, 0x2c000
	s_mov_b32 s44, 0x2e000
	s_mov_b32 s45, 0x30000
	s_mov_b32 s48, 0x32000
	s_mov_b32 s49, 0x34000
	s_mov_b32 s60, 0x36000
	s_mov_b32 s61, 0x38000
	s_mov_b32 s95, 0x3a000
	s_mov_b32 s3, 0x3c000
	s_mov_b32 s37, 0x3e000
	s_movk_i32 s38, 0x1800
	s_mov_b32 s19, 0
	v_cmp_eq_u32_e64 s[0:1], 0, v1
	v_readlane_b32 s18, v254, 17
	s_branch .LBB0_11

; __device__ __forceinline__ void p0_prologue(const Params& p, const Frame& F0) {
;     ...
;     for (int it = gw; it < NITEMS; it += NGW) {
;         int r = it;
;         if (r < I_IN) { const int kb = r / 48, nb = r % 48; transpose_item(p.in[8], DM, DIN, Win_t, DM, 64 * kb, 32 * nb, win_dest_row(32 * nb), scr, F.lane); continue; } r -= I_IN;
.LBB0_10:
	s_bitcmp1_b32 s26, 2
	s_cselect_b32 s98, 0x7fc, 4
	s_add_i32 s26, s26, s98
	s_lshl_b32 s99, s98, 5
	s_add_i32 s27, s27, s99
	s_lshl_b32 s99, s98, 6
	s_add_i32 s29, s29, s99
	s_lshl_b32 s99, s98, 1
	s_add_i32 s31, s31, s99
	s_lshl_b32 s99, s98, 2
	s_add_i32 s35, s35, s99
	s_cmpk_gt_i32 s26, 0x257f
	s_cbranch_scc1 .LBB0_156
